# SWA and NA tile loops: the tile's eight K-fragment ds_reads issued at the loop head, ahead of the loader/address block
# baseline (speedup 1.0000x reference)
.LBB0_242:
	s_and_b32 s10, s31, 0x4000
	v_add3_u32 v94, s10, v108, v107
	v_add3_u32 v95, s10, v109, v107
	v_add3_u32 v117, s10, v110, v107
	v_add3_u32 v118, s10, v111, v107
	ds_read_b128 v[148:151], v94
	ds_read_b128 v[152:155], v95
	ds_read_b128 v[156:159], v117
	ds_read_b128 v[160:163], v118
	ds_read_b128 v[164:167], v94 offset:4096
	ds_read_b128 v[168:171], v95 offset:4096
	ds_read_b128 v[172:175], v117 offset:4096
	ds_read_b128 v[176:179], v118 offset:4096
	s_add_i32 s44, s45, 1
	s_cmp_ge_i32 s45, s28
	s_cselect_b64 s[38:39], -1, 0
	s_and_b64 vcc, exec, s[38:39]
	s_cbranch_vccnz .LBB0_246
	s_cmp_lt_u32 s45, 7
	s_cselect_b64 s[40:41], -1, 0
	s_add_i32 s10, s24, s45
	s_add_i32 s10, s10, -9
	s_and_b64 s[42:43], s[40:41], exec
	s_cselect_b32 s11, s44, s10
	s_cselect_b32 s42, s25, s3
	s_lshl_b32 s11, s11, 6
	s_add_i32 s11, s11, s42
	s_and_b64 vcc, s[40:41], exec
	v_add_u32_e32 v50, s11, v98
	s_cselect_b32 s11, s87, s71
	s_cselect_b32 s40, s86, s70
	v_mov_b32_e32 v49, s11
	s_cselect_b32 s11, s82, s84
	v_mov_b32_e32 v48, s40
	v_mad_i64_i32 v[50:51], s[40:41], v50, s11, 0
	v_lshl_add_u64 v[48:49], v[50:51], 1, v[48:49]
	v_lshl_add_u64 v[48:49], v[48:49], 0, s[0:1]
	v_lshl_add_u64 v[48:49], v[14:15], 1, v[48:49]
	global_load_dwordx4 v[84:87], v[48:49], off
	s_mov_b64 s[42:43], s[82:83]
	s_mov_b64 s[40:41], s[90:91]
	s_mov_b32 s11, s44
	s_mov_b32 s43, s25
	s_cbranch_vccnz .LBB0_245
	s_mov_b64 s[42:43], s[84:85]
	s_mov_b64 s[40:41], s[6:7]
	s_mov_b32 s11, s10
	s_mov_b32 s43, s3

.LBB0_251:
	s_and_b32 s10, s31, 0x4000
	s_andn2_b64 vcc, exec, s[40:41]
	s_waitcnt lgkmcnt(7)
	v_mfma_f32_32x32x16_bf16 v[48:63], v[148:151], v[2:5], 0
	s_waitcnt lgkmcnt(6)
	v_mfma_f32_32x32x16_bf16 v[48:63], v[152:155], v[6:9], v[48:63]
	s_waitcnt lgkmcnt(5)
	v_mfma_f32_32x32x16_bf16 v[48:63], v[156:159], v[10:13], v[48:63]
	s_waitcnt lgkmcnt(4)
	v_mfma_f32_32x32x16_bf16 v[48:63], v[160:163], v[80:83], v[48:63]
	s_waitcnt lgkmcnt(3)
	v_mfma_f32_32x32x16_bf16 v[64:79], v[164:167], v[2:5], 0
	s_waitcnt lgkmcnt(2)
	v_mfma_f32_32x32x16_bf16 v[64:79], v[168:171], v[6:9], v[64:79]
	s_waitcnt lgkmcnt(1)
	v_mfma_f32_32x32x16_bf16 v[64:79], v[172:175], v[10:13], v[64:79]
	s_waitcnt lgkmcnt(0)
	v_mfma_f32_32x32x16_bf16 v[64:79], v[176:179], v[80:83], v[64:79]
	s_cbranch_vccnz .LBB0_253
	v_add_u32_e32 v94, s29, v116
	v_add_u32_e32 v95, 0xfffffcff, v94
	s_movk_i32 s2, 0xfefe
	v_cmp_lt_u32_e32 vcc, s2, v95
	v_add_u32_e32 v95, 0xfffffd1f, v94
	s_nop 2
	v_cndmask_b32_e32 v48, v213, v48, vcc
	v_cmp_lt_u32_e32 vcc, s2, v95
	v_add_u32_e32 v95, 0xfffffd00, v94
	s_nop 0
	v_cndmask_b32_e32 v64, v213, v64, vcc
	v_cmp_lt_u32_e32 vcc, s2, v95
	v_add_u32_e32 v95, 0xfffffd20, v94
	s_nop 0
	v_cndmask_b32_e32 v49, v213, v49, vcc
	v_cmp_lt_u32_e32 vcc, s2, v95
	v_add_u32_e32 v95, 0xfffffd01, v94
	s_nop 0
	v_cndmask_b32_e32 v65, v213, v65, vcc
	v_cmp_lt_u32_e32 vcc, s2, v95
	v_add_u32_e32 v95, 0xfffffd21, v94
	s_nop 0
	v_cndmask_b32_e32 v50, v213, v50, vcc
	v_cmp_lt_u32_e32 vcc, s2, v95
	v_add_u32_e32 v95, 0xfffffd02, v94
	s_nop 0
	v_cndmask_b32_e32 v66, v213, v66, vcc
	v_cmp_lt_u32_e32 vcc, s2, v95
	v_add_u32_e32 v95, 0xfffffd22, v94
	s_nop 0
	v_cndmask_b32_e32 v51, v213, v51, vcc
	v_cmp_lt_u32_e32 vcc, s2, v95
	v_add_u32_e32 v95, 0xfffffd07, v94
	s_nop 0
	v_cndmask_b32_e32 v67, v213, v67, vcc
	v_cmp_lt_u32_e32 vcc, s2, v95
	v_add_u32_e32 v95, 0xfffffd27, v94
	s_nop 0
	v_cndmask_b32_e32 v52, v213, v52, vcc
	v_cmp_lt_u32_e32 vcc, s2, v95
	v_add_u32_e32 v95, 0xfffffd08, v94
	s_nop 0
	v_cndmask_b32_e32 v68, v213, v68, vcc
	v_cmp_lt_u32_e32 vcc, s2, v95
	v_add_u32_e32 v95, 0xfffffd28, v94
	s_nop 0
	v_cndmask_b32_e32 v53, v213, v53, vcc
	v_cmp_lt_u32_e32 vcc, s2, v95
	v_add_u32_e32 v95, 0xfffffd09, v94
	s_nop 0
	v_cndmask_b32_e32 v69, v213, v69, vcc
	v_cmp_lt_u32_e32 vcc, s2, v95
	v_add_u32_e32 v95, 0xfffffd29, v94
	s_nop 0
	v_cndmask_b32_e32 v54, v213, v54, vcc
	v_cmp_lt_u32_e32 vcc, s2, v95
	v_add_u32_e32 v95, 0xfffffd0a, v94
	s_nop 0
	v_cndmask_b32_e32 v70, v213, v70, vcc
	v_cmp_lt_u32_e32 vcc, s2, v95
	v_add_u32_e32 v95, 0xfffffd2a, v94
	s_nop 0
	v_cndmask_b32_e32 v55, v213, v55, vcc
	v_cmp_lt_u32_e32 vcc, s2, v95
	v_add_u32_e32 v95, 0xfffffd0f, v94
	s_nop 0
	v_cndmask_b32_e32 v71, v213, v71, vcc
	v_cmp_lt_u32_e32 vcc, s2, v95
	v_add_u32_e32 v95, 0xfffffd2f, v94
	s_nop 0
	v_cndmask_b32_e32 v56, v213, v56, vcc
	v_cmp_lt_u32_e32 vcc, s2, v95
	v_add_u32_e32 v95, 0xfffffd10, v94
	s_nop 0
	v_cndmask_b32_e32 v72, v213, v72, vcc
	v_cmp_lt_u32_e32 vcc, s2, v95
	v_add_u32_e32 v95, 0xfffffd30, v94
	s_nop 0
	v_cndmask_b32_e32 v57, v213, v57, vcc
	v_cmp_lt_u32_e32 vcc, s2, v95
	v_add_u32_e32 v95, 0xfffffd11, v94
	s_nop 0
	v_cndmask_b32_e32 v73, v213, v73, vcc
	v_cmp_lt_u32_e32 vcc, s2, v95
	v_add_u32_e32 v95, 0xfffffd31, v94
	s_nop 0
	v_cndmask_b32_e32 v58, v213, v58, vcc
	v_cmp_lt_u32_e32 vcc, s2, v95
	v_add_u32_e32 v95, 0xfffffd12, v94
	s_nop 0
	v_cndmask_b32_e32 v74, v213, v74, vcc
	v_cmp_lt_u32_e32 vcc, s2, v95
	v_add_u32_e32 v95, 0xfffffd32, v94
	s_nop 0
	v_cndmask_b32_e32 v59, v213, v59, vcc
	v_cmp_lt_u32_e32 vcc, s2, v95
	v_add_u32_e32 v95, 0xfffffd17, v94
	s_nop 0
	v_cndmask_b32_e32 v75, v213, v75, vcc
	v_cmp_lt_u32_e32 vcc, s2, v95
	v_add_u32_e32 v95, 0xfffffd37, v94
	s_nop 0
	v_cndmask_b32_e32 v60, v213, v60, vcc
	v_cmp_lt_u32_e32 vcc, s2, v95
	v_add_u32_e32 v95, 0xfffffd18, v94
	s_nop 0
	v_cndmask_b32_e32 v76, v213, v76, vcc
	v_cmp_lt_u32_e32 vcc, s2, v95
	v_add_u32_e32 v95, 0xfffffd38, v94
	s_nop 0
	v_cndmask_b32_e32 v61, v213, v61, vcc
	v_cmp_lt_u32_e32 vcc, s2, v95
	v_add_u32_e32 v95, 0xfffffd19, v94
	s_nop 0
	v_cndmask_b32_e32 v77, v213, v77, vcc
	v_cmp_lt_u32_e32 vcc, s2, v95
	v_add_u32_e32 v95, 0xfffffd39, v94
	v_add_u32_e32 v94, 0xfffffd1a, v94
	v_cndmask_b32_e32 v62, v213, v62, vcc
	v_cmp_lt_u32_e32 vcc, s2, v95
	s_nop 1
	v_cndmask_b32_e32 v78, v213, v78, vcc
	v_cmp_lt_u32_e32 vcc, s2, v94
	v_add_u32_e32 v94, s29, v115
	v_add_u32_e32 v94, 0xfffffd3a, v94
	v_cndmask_b32_e32 v63, v213, v63, vcc
	v_cmp_lt_u32_e32 vcc, s2, v94
	s_nop 1
	v_cndmask_b32_e32 v79, v213, v79, vcc

.LBB0_281:
	s_add_i32 s10, s24, 0xffffc000
	s_and_b32 s10, s10, 0x4000
	v_add3_u32 v94, s10, v109, v108
	v_add3_u32 v95, s10, v110, v108
	v_add3_u32 v130, s10, v111, v108
	v_add3_u32 v131, s10, v112, v108
	ds_read_b128 v[148:151], v94
	ds_read_b128 v[152:155], v95
	ds_read_b128 v[156:159], v130
	ds_read_b128 v[160:163], v131
	ds_read_b128 v[164:167], v94 offset:4096
	ds_read_b128 v[168:171], v95 offset:4096
	ds_read_b128 v[172:175], v130 offset:4096
	ds_read_b128 v[176:179], v131 offset:4096
	s_cmp_lt_u32 s28, 7
	s_cselect_b64 vcc, -1, 0
	v_add_u32_e32 v34, s29, v129
	s_and_b64 s[10:11], vcc, exec
	v_cndmask_b32_e32 v36, v127, v34, vcc
	s_cselect_b32 s10, s87, s71
	s_cselect_b32 s11, s86, s70
	s_cselect_b32 s25, s82, s84
	v_mov_b32_e32 v34, s11
	v_mov_b32_e32 v35, s10
	v_mad_i64_i32 v[36:37], s[10:11], v36, s25, 0
	v_lshl_add_u64 v[34:35], v[36:37], 1, v[34:35]
	v_lshl_add_u64 v[34:35], v[34:35], 0, s[0:1]
	v_lshl_add_u64 v[34:35], v[92:93], 1, v[34:35]
	global_load_dwordx4 v[82:85], v[34:35], off
	v_add_u32_e32 v34, s29, v128
	v_cndmask_b32_e32 v36, v126, v34, vcc
	s_cselect_b32 s10, s91, s7
	s_cselect_b32 s11, s90, s6
	v_mov_b32_e32 v34, s11
	v_mov_b32_e32 v35, s10
	v_mad_i64_i32 v[36:37], s[10:11], v36, s25, 0
	v_lshl_add_u64 v[34:35], v[36:37], 1, v[34:35]
	v_lshl_add_u64 v[34:35], v[34:35], 0, s[0:1]
	v_lshl_add_u64 v[34:35], v[34:35], 0, v[0:1]
	global_load_dwordx4 v[86:89], v[34:35], off
	s_cmp_gt_u32 s28, 7
	s_cselect_b64 s[72:73], -1, 0
	s_cmp_lt_u32 s28, 8
	s_cselect_b64 s[10:11], -1, 0
	s_and_b64 vcc, exec, s[10:11]
	s_cbranch_vccnz .LBB0_283
	s_add_i32 s10, s3, 1
	s_cmp_ge_u32 s10, s31
	s_cselect_b64 s[10:11], -1, 0
	s_cmp_lt_u32 s3, s85
	s_cselect_b64 s[26:27], -1, 0
	s_and_b64 s[10:11], s[10:11], s[26:27]
.LBB0_283:
	s_andn2_b64 vcc, exec, s[10:11]
	s_cbranch_vccnz .LBB0_280
	s_add_i32 s10, s24, 0xffffc000
	s_and_b32 s10, s10, 0x4000
	s_andn2_b64 vcc, exec, s[72:73]
	s_waitcnt lgkmcnt(7)
	v_mfma_f32_32x32x16_bf16 v[34:49], v[148:151], v[78:81], 0
	s_waitcnt lgkmcnt(6)
	v_mfma_f32_32x32x16_bf16 v[34:49], v[152:155], v[74:77], v[34:49]
	s_waitcnt lgkmcnt(5)
	v_mfma_f32_32x32x16_bf16 v[34:49], v[156:159], v[70:73], v[34:49]
	s_waitcnt lgkmcnt(4)
	v_mfma_f32_32x32x16_bf16 v[34:49], v[160:163], v[66:69], v[34:49]
	s_waitcnt lgkmcnt(3)
	v_mfma_f32_32x32x16_bf16 v[50:65], v[164:167], v[78:81], 0
	s_waitcnt lgkmcnt(2)
	v_mfma_f32_32x32x16_bf16 v[50:65], v[168:171], v[74:77], v[50:65]
	s_waitcnt lgkmcnt(1)
	v_mfma_f32_32x32x16_bf16 v[50:65], v[172:175], v[70:73], v[50:65]
	s_waitcnt lgkmcnt(0)
	v_mfma_f32_32x32x16_bf16 v[50:65], v[176:179], v[66:69], v[50:65]
	s_cbranch_vccnz .LBB0_286
	v_cmp_ge_i32_e32 vcc, s3, v98
	v_cmp_lt_i32_e64 s[72:73], s3, v106
	s_and_b64 s[26:27], vcc, s[72:73]
	s_add_i32 s11, s3, 1
	v_cmp_ge_i32_e32 vcc, s11, v98
	v_cmp_lt_i32_e64 s[72:73], s11, v106
	s_and_b64 s[72:73], vcc, s[72:73]
	v_add_u32_e32 v94, s29, v125
	s_and_b64 vcc, s[26:27], s[68:69]
	v_add_u32_e32 v95, 0xffffff2f, v94
	v_cndmask_b32_e32 v95, 0, v95, vcc
	v_lshl_add_u32 v95, v95, 2, 0
	ds_read_b32 v148, v95 offset:32768
	s_and_b64 vcc, s[26:27], s[66:67]
	v_add_u32_e32 v95, 0xffffff30, v94
	v_cndmask_b32_e32 v95, 0, v95, vcc
	v_lshl_add_u32 v95, v95, 2, 0
	ds_read_b32 v149, v95 offset:32768
	s_and_b64 vcc, s[26:27], s[64:65]
	v_add_u32_e32 v95, 0xffffff31, v94
	v_cndmask_b32_e32 v95, 0, v95, vcc
	v_lshl_add_u32 v95, v95, 2, 0
	ds_read_b32 v150, v95 offset:32768
	s_and_b64 vcc, s[26:27], s[62:63]
	v_add_u32_e32 v95, 0xffffff32, v94
	v_cndmask_b32_e32 v95, 0, v95, vcc
	v_lshl_add_u32 v95, v95, 2, 0
	ds_read_b32 v151, v95 offset:32768
	s_and_b64 vcc, s[26:27], s[60:61]
	v_add_u32_e32 v95, 0xffffff37, v94
	v_cndmask_b32_e32 v95, 0, v95, vcc
	v_lshl_add_u32 v95, v95, 2, 0
	ds_read_b32 v152, v95 offset:32768
	s_and_b64 vcc, s[26:27], s[58:59]
	v_add_u32_e32 v95, 0xffffff38, v94
	v_cndmask_b32_e32 v95, 0, v95, vcc
	v_lshl_add_u32 v95, v95, 2, 0
	ds_read_b32 v153, v95 offset:32768
	s_and_b64 vcc, s[26:27], s[56:57]
	v_add_u32_e32 v95, 0xffffff39, v94
	v_cndmask_b32_e32 v95, 0, v95, vcc
	v_lshl_add_u32 v95, v95, 2, 0
	ds_read_b32 v154, v95 offset:32768
	s_and_b64 vcc, s[26:27], s[54:55]
	v_add_u32_e32 v95, 0xffffff3a, v94
	v_cndmask_b32_e32 v95, 0, v95, vcc
	v_lshl_add_u32 v95, v95, 2, 0
	ds_read_b32 v155, v95 offset:32768
	s_and_b64 vcc, s[26:27], s[52:53]
	v_add_u32_e32 v95, 0xffffff3f, v94
	v_cndmask_b32_e32 v95, 0, v95, vcc
	v_lshl_add_u32 v95, v95, 2, 0
	ds_read_b32 v156, v95 offset:32768
	s_and_b64 vcc, s[26:27], s[50:51]
	v_add_u32_e32 v95, 0xffffff40, v94
	v_cndmask_b32_e32 v95, 0, v95, vcc
	v_lshl_add_u32 v95, v95, 2, 0
	ds_read_b32 v157, v95 offset:32768
	s_and_b64 vcc, s[26:27], s[48:49]
	v_add_u32_e32 v95, 0xffffff41, v94
	v_cndmask_b32_e32 v95, 0, v95, vcc
	v_lshl_add_u32 v95, v95, 2, 0
	ds_read_b32 v158, v95 offset:32768
	s_and_b64 vcc, s[26:27], s[46:47]
	v_add_u32_e32 v95, 0xffffff42, v94
	v_cndmask_b32_e32 v95, 0, v95, vcc
	v_lshl_add_u32 v95, v95, 2, 0
	ds_read_b32 v159, v95 offset:32768
	s_waitcnt lgkmcnt(11)
	s_and_b64 vcc, s[26:27], s[68:69]
	v_add_f32_e32 v34, v34, v148
	v_cndmask_b32_e32 v34, v213, v34, vcc
	s_and_b64 vcc, s[26:27], s[44:45]
	v_add_u32_e32 v95, 0xffffff47, v94
	v_cndmask_b32_e32 v95, 0, v95, vcc
	v_lshl_add_u32 v95, v95, 2, 0
	ds_read_b32 v148, v95 offset:32768
	s_waitcnt lgkmcnt(11)
	s_and_b64 vcc, s[26:27], s[66:67]
	v_add_f32_e32 v35, v35, v149
	v_cndmask_b32_e32 v35, v213, v35, vcc
	s_and_b64 vcc, s[26:27], s[42:43]
	v_add_u32_e32 v95, 0xffffff48, v94
	v_cndmask_b32_e32 v95, 0, v95, vcc
	v_lshl_add_u32 v95, v95, 2, 0
	ds_read_b32 v149, v95 offset:32768
	s_waitcnt lgkmcnt(11)
	s_and_b64 vcc, s[26:27], s[64:65]
	v_add_f32_e32 v36, v36, v150
	v_cndmask_b32_e32 v36, v213, v36, vcc
	s_and_b64 vcc, s[26:27], s[40:41]
	v_add_u32_e32 v95, 0xffffff49, v94
	v_cndmask_b32_e32 v95, 0, v95, vcc
	v_lshl_add_u32 v95, v95, 2, 0
	ds_read_b32 v150, v95 offset:32768
	s_waitcnt lgkmcnt(11)
	s_and_b64 vcc, s[26:27], s[62:63]
	v_add_f32_e32 v37, v37, v151
	v_cndmask_b32_e32 v37, v213, v37, vcc
	s_and_b64 vcc, s[26:27], s[38:39]
	v_add_u32_e32 v95, 0xffffff4a, v94
	v_cndmask_b32_e32 v95, 0, v95, vcc
	v_lshl_add_u32 v95, v95, 2, 0
	ds_read_b32 v151, v95 offset:32768
	s_waitcnt lgkmcnt(11)
	s_and_b64 vcc, s[26:27], s[60:61]
	v_add_f32_e32 v38, v38, v152
	v_cndmask_b32_e32 v38, v213, v38, vcc
	s_and_b64 vcc, s[72:73], s[68:69]
	v_add_u32_e32 v95, 0xffffff4f, v94
	v_cndmask_b32_e32 v95, 0, v95, vcc
	v_lshl_add_u32 v95, v95, 2, 0
	ds_read_b32 v152, v95 offset:32768
	s_waitcnt lgkmcnt(11)
	s_and_b64 vcc, s[26:27], s[58:59]
	v_add_f32_e32 v39, v39, v153
	v_cndmask_b32_e32 v39, v213, v39, vcc
	s_and_b64 vcc, s[72:73], s[66:67]
	v_add_u32_e32 v95, 0xffffff50, v94
	v_cndmask_b32_e32 v95, 0, v95, vcc
	v_lshl_add_u32 v95, v95, 2, 0
	ds_read_b32 v153, v95 offset:32768
	s_waitcnt lgkmcnt(11)
	s_and_b64 vcc, s[26:27], s[56:57]
	v_add_f32_e32 v40, v40, v154
	v_cndmask_b32_e32 v40, v213, v40, vcc
	s_and_b64 vcc, s[72:73], s[64:65]
	v_add_u32_e32 v95, 0xffffff51, v94
	v_cndmask_b32_e32 v95, 0, v95, vcc
	v_lshl_add_u32 v95, v95, 2, 0
	ds_read_b32 v154, v95 offset:32768
	s_waitcnt lgkmcnt(11)
	s_and_b64 vcc, s[26:27], s[54:55]
	v_add_f32_e32 v41, v41, v155
	v_cndmask_b32_e32 v41, v213, v41, vcc
	s_and_b64 vcc, s[72:73], s[62:63]
	v_add_u32_e32 v95, 0xffffff52, v94
	v_cndmask_b32_e32 v95, 0, v95, vcc
	v_lshl_add_u32 v95, v95, 2, 0
	ds_read_b32 v155, v95 offset:32768
	s_waitcnt lgkmcnt(11)
	s_and_b64 vcc, s[26:27], s[52:53]
	v_add_f32_e32 v42, v42, v156
	v_cndmask_b32_e32 v42, v213, v42, vcc
	s_and_b64 vcc, s[72:73], s[60:61]
	v_add_u32_e32 v95, 0xffffff57, v94
	v_cndmask_b32_e32 v95, 0, v95, vcc
	v_lshl_add_u32 v95, v95, 2, 0
	ds_read_b32 v156, v95 offset:32768
	s_waitcnt lgkmcnt(11)
	s_and_b64 vcc, s[26:27], s[50:51]
	v_add_f32_e32 v43, v43, v157
	v_cndmask_b32_e32 v43, v213, v43, vcc
	s_and_b64 vcc, s[72:73], s[58:59]
	v_add_u32_e32 v95, 0xffffff58, v94
	v_cndmask_b32_e32 v95, 0, v95, vcc
	v_lshl_add_u32 v95, v95, 2, 0
	ds_read_b32 v157, v95 offset:32768
	s_waitcnt lgkmcnt(11)
	s_and_b64 vcc, s[26:27], s[48:49]
	v_add_f32_e32 v44, v44, v158
	v_cndmask_b32_e32 v44, v213, v44, vcc
	s_and_b64 vcc, s[72:73], s[56:57]
	v_add_u32_e32 v95, 0xffffff59, v94
	v_cndmask_b32_e32 v95, 0, v95, vcc
	v_lshl_add_u32 v95, v95, 2, 0
	ds_read_b32 v158, v95 offset:32768
	s_waitcnt lgkmcnt(11)
	s_and_b64 vcc, s[26:27], s[46:47]
	v_add_f32_e32 v45, v45, v159
	v_cndmask_b32_e32 v45, v213, v45, vcc
	s_and_b64 vcc, s[72:73], s[54:55]
	v_add_u32_e32 v95, 0xffffff5a, v94
	v_cndmask_b32_e32 v95, 0, v95, vcc
	v_lshl_add_u32 v95, v95, 2, 0
	ds_read_b32 v159, v95 offset:32768
	s_waitcnt lgkmcnt(11)
	s_and_b64 vcc, s[26:27], s[44:45]
	v_add_f32_e32 v46, v46, v148
	v_cndmask_b32_e32 v46, v213, v46, vcc
	s_and_b64 vcc, s[72:73], s[52:53]
	v_add_u32_e32 v95, 0xffffff5f, v94
	v_cndmask_b32_e32 v95, 0, v95, vcc
	v_lshl_add_u32 v95, v95, 2, 0
	ds_read_b32 v148, v95 offset:32768
	s_waitcnt lgkmcnt(11)
	s_and_b64 vcc, s[26:27], s[42:43]
	v_add_f32_e32 v47, v47, v149
	v_cndmask_b32_e32 v47, v213, v47, vcc
	s_and_b64 vcc, s[72:73], s[50:51]
	v_add_u32_e32 v95, 0xffffff60, v94
	v_cndmask_b32_e32 v95, 0, v95, vcc
	v_lshl_add_u32 v95, v95, 2, 0
	ds_read_b32 v149, v95 offset:32768
	s_waitcnt lgkmcnt(11)
	s_and_b64 vcc, s[26:27], s[40:41]
	v_add_f32_e32 v48, v48, v150
	v_cndmask_b32_e32 v48, v213, v48, vcc
	s_and_b64 vcc, s[72:73], s[48:49]
	v_add_u32_e32 v95, 0xffffff61, v94
	v_cndmask_b32_e32 v95, 0, v95, vcc
	v_lshl_add_u32 v95, v95, 2, 0
	ds_read_b32 v150, v95 offset:32768
	s_waitcnt lgkmcnt(11)
	s_and_b64 vcc, s[26:27], s[38:39]
	v_add_f32_e32 v49, v49, v151
	v_cndmask_b32_e32 v49, v213, v49, vcc
	s_and_b64 vcc, s[72:73], s[46:47]
	v_add_u32_e32 v95, 0xffffff62, v94
	v_cndmask_b32_e32 v95, 0, v95, vcc
	v_lshl_add_u32 v95, v95, 2, 0
	ds_read_b32 v151, v95 offset:32768
	s_waitcnt lgkmcnt(11)
	s_and_b64 vcc, s[72:73], s[68:69]
	v_add_f32_e32 v50, v50, v152
	v_cndmask_b32_e32 v50, v213, v50, vcc
	s_and_b64 vcc, s[72:73], s[44:45]
	v_add_u32_e32 v95, 0xffffff67, v94
	v_cndmask_b32_e32 v95, 0, v95, vcc
	v_lshl_add_u32 v95, v95, 2, 0
	ds_read_b32 v152, v95 offset:32768
	s_waitcnt lgkmcnt(11)
	s_and_b64 vcc, s[72:73], s[66:67]
	v_add_f32_e32 v51, v51, v153
	v_cndmask_b32_e32 v51, v213, v51, vcc
	s_and_b64 vcc, s[72:73], s[42:43]
	v_add_u32_e32 v95, 0xffffff68, v94
	v_cndmask_b32_e32 v95, 0, v95, vcc
	v_lshl_add_u32 v95, v95, 2, 0
	ds_read_b32 v153, v95 offset:32768
	s_waitcnt lgkmcnt(11)
	s_and_b64 vcc, s[72:73], s[64:65]
	v_add_f32_e32 v52, v52, v154
	v_cndmask_b32_e32 v52, v213, v52, vcc
	s_and_b64 vcc, s[72:73], s[40:41]
	v_add_u32_e32 v95, 0xffffff69, v94
	v_cndmask_b32_e32 v95, 0, v95, vcc
	v_lshl_add_u32 v95, v95, 2, 0
	ds_read_b32 v154, v95 offset:32768
	s_waitcnt lgkmcnt(11)
	s_and_b64 vcc, s[72:73], s[62:63]
	v_add_f32_e32 v53, v53, v155
	v_cndmask_b32_e32 v53, v213, v53, vcc
	s_and_b64 vcc, s[72:73], s[38:39]
	v_add_u32_e32 v95, 0xffffff6a, v94
	v_cndmask_b32_e32 v95, 0, v95, vcc
	v_lshl_add_u32 v95, v95, 2, 0
	ds_read_b32 v155, v95 offset:32768
	s_waitcnt lgkmcnt(11)
	s_and_b64 vcc, s[72:73], s[60:61]
	v_add_f32_e32 v54, v54, v156
	v_cndmask_b32_e32 v54, v213, v54, vcc
	s_waitcnt lgkmcnt(10)
	s_and_b64 vcc, s[72:73], s[58:59]
	v_add_f32_e32 v55, v55, v157
	v_cndmask_b32_e32 v55, v213, v55, vcc
	s_waitcnt lgkmcnt(9)
	s_and_b64 vcc, s[72:73], s[56:57]
	v_add_f32_e32 v56, v56, v158
	v_cndmask_b32_e32 v56, v213, v56, vcc
	s_waitcnt lgkmcnt(8)
	s_and_b64 vcc, s[72:73], s[54:55]
	v_add_f32_e32 v57, v57, v159
	v_cndmask_b32_e32 v57, v213, v57, vcc
	s_waitcnt lgkmcnt(7)
	s_and_b64 vcc, s[72:73], s[52:53]
	v_add_f32_e32 v58, v58, v148
	v_cndmask_b32_e32 v58, v213, v58, vcc
	s_waitcnt lgkmcnt(6)
	s_and_b64 vcc, s[72:73], s[50:51]
	v_add_f32_e32 v59, v59, v149
	v_cndmask_b32_e32 v59, v213, v59, vcc
	s_waitcnt lgkmcnt(5)
	s_and_b64 vcc, s[72:73], s[48:49]
	v_add_f32_e32 v60, v60, v150
	v_cndmask_b32_e32 v60, v213, v60, vcc
	s_waitcnt lgkmcnt(4)
	s_and_b64 vcc, s[72:73], s[46:47]
	v_add_f32_e32 v61, v61, v151
	v_cndmask_b32_e32 v61, v213, v61, vcc
	s_waitcnt lgkmcnt(3)
	s_and_b64 vcc, s[72:73], s[44:45]
	v_add_f32_e32 v62, v62, v152
	v_cndmask_b32_e32 v62, v213, v62, vcc
	s_waitcnt lgkmcnt(2)
	s_and_b64 vcc, s[72:73], s[42:43]
	v_add_f32_e32 v63, v63, v153
	v_cndmask_b32_e32 v63, v213, v63, vcc
	s_waitcnt lgkmcnt(1)
	s_and_b64 vcc, s[72:73], s[40:41]
	v_add_f32_e32 v64, v64, v154
	v_cndmask_b32_e32 v64, v213, v64, vcc
	s_waitcnt lgkmcnt(0)
	s_and_b64 vcc, s[72:73], s[38:39]
	v_add_f32_e32 v65, v65, v155
	v_cndmask_b32_e32 v65, v213, v65, vcc
